# more setup de-serialisation: SWA K/V staging unrolled (three tiles in flight), MoBA merge loop issues all nine partial loads up front
# speedup vs baseline: 1.0149x; 1.0032x over previous
; #define LAS __attribute__((address_space(3)))
; __device__ __forceinline__ void swa_unit(lbyte* lds, const bf16* QKV, bf16* AO, const float* rel_bias, const float* sinks, int b, int hkv, int qb) {
;     ...
; #pragma unroll
;     for (int i = tid; i < 192 * 8; i += NT) { const int row = i >> 3, ch = i & 7, key = k0 + row; u32x4 kv = (u32x4){0u, 0u, 0u, 0u}, vv = kv;
;         if (key >= 0) { kv = *(const u32x4*)(QKV + (rowbase + key) * LD + kcol + ch * 8); vv = *(const u32x4*)(QKV + (rowbase + key) * LD + vcol + ch * 8); }
;         *(LAS u32x4*)(lds + SW_K + row * KP64 + ch * 16) = kv;
;         LAS unsigned short* vp = (LAS unsigned short*)(lds + SW_V + (ch * 8) * SW_VP + row * 2);
;         vp[0 * (SW_VP / 2)] = (unsigned short)(vv.x & 0xffffu); vp[1 * (SW_VP / 2)] = (unsigned short)(vv.x >> 16); vp[2 * (SW_VP / 2)] = (unsigned short)(vv.y & 0xffffu); vp[3 * (SW_VP / 2)] = (unsigned short)(vv.y >> 16);
;         vp[4 * (SW_VP / 2)] = (unsigned short)(vv.z & 0xffffu); vp[5 * (SW_VP / 2)] = (unsigned short)(vv.z >> 16); vp[6 * (SW_VP / 2)] = (unsigned short)(vv.w & 0xffffu); vp[7 * (SW_VP / 2)] = (unsigned short)(vv.w >> 16); }
.LBB0_527:
	v_mov_b32_e32 v0, s42
	ds_read_b64 v[2:3], v0
	s_ashr_i32 s4, s10, 31
	s_lshr_b32 s4, s4, 29
	s_add_i32 s8, s10, s4
	v_mov_b32_e32 v0, s37
	s_and_b32 s4, s8, 0xfff8
	s_waitcnt lgkmcnt(0)
	v_readfirstlane_b32 s21, v3
	v_readfirstlane_b32 s22, v2
	ds_read_b64 v[2:3], v0
	s_sub_i32 s5, s10, s4
	s_bfe_u32 s4, s5, 0x10007
	s_add_i32 s6, s5, s4
	s_bfe_i32 s4, s6, 0x80000
	s_and_b32 s6, s6, 0xfe
	v_mov_b32_e32 v0, s27
	s_sext_i32_i16 s4, s4
	s_sub_i32 s5, s5, s6
	s_waitcnt lgkmcnt(0)
	v_readfirstlane_b32 s7, v3
	v_readfirstlane_b32 s6, v2
	ds_read_b64 v[2:3], v0
	s_lshr_b32 s4, s4, 1
	s_add_u32 s15, s22, 0xac00000
	s_addc_u32 s20, s21, 0
	s_lshl_b32 s11, s8, 3
	s_sext_i32_i8 s26, s5
	v_mov_b32_e32 v11, v232
	s_bfe_i64 s[4:5], s[4:5], 0x100000
	s_andn2_b32 s11, s11, 63
	s_movk_i32 s8, 0x600
	s_waitcnt lgkmcnt(0)
	v_readfirstlane_b32 s23, v3
	v_readfirstlane_b32 s24, v2
	s_lshl_b64 s[4:5], s[4:5], 13
	v_readfirstlane_b32 s25, v11
	s_add_i32 s14, s11, 0xffffff80
	v_cmp_gt_i32_e32 vcc, s8, v11
	s_and_saveexec_b64 s[8:9], vcc
	s_cbranch_execz .LBB0_532
	s_lshl_b32 s12, s26, 6
	s_ashr_i32 s13, s12, 31
	s_lshl_b64 s[12:13], s[12:13], 1
	v_and_b32_e32 v2, 7, v11
	s_add_u32 s12, s15, s12
	v_lshlrev_b32_e32 v0, 4, v2
	s_addc_u32 s13, s20, s13
	v_add_u32_e32 v10, 0, v0
	s_movk_i32 s16, 0xc70
	v_mad_u32_u24 v14, v2, s16, v10
	v_lshl_add_u64 v[12:13], s[12:13], 0, v[0:1]
	s_mov_b64 s[12:13], 0
	v_mov_b32_e32 v15, v11
	v_ashrrev_i32_e32 v16, 3, v11
	v_mad_u64_u32 v[18:19], s[16:17], v16, s73, v[10:11]
	v_lshl_add_u32 v17, v16, 1, v14
	v_add_u32_e32 v15, s14, v16
	v_mov_b32_e32 v20, 0
	v_mov_b32_e32 v21, 0
	v_mov_b32_e32 v22, 0
	v_mov_b32_e32 v23, 0
	v_mov_b32_e32 v24, 0
	v_mov_b32_e32 v25, 0
	v_mov_b32_e32 v26, 0
	v_mov_b32_e32 v27, 0
	v_mov_b32_e32 v0, v15
	v_cmp_lt_i32_e32 vcc, -1, v0
	s_and_saveexec_b64 s[16:17], vcc
	s_cbranch_execz .Lswakv_skip0
	v_lshl_add_u64 v[2:3], s[4:5], 0, v[0:1]
	v_mad_u64_u32 v[4:5], s[30:31], v2, s72, v[12:13]
	v_mad_i32_i24 v5, v3, s72, v5
	global_load_dwordx4 v[20:23], v[4:5], off offset:2048
	s_nop 0
	global_load_dwordx4 v[24:27], v[4:5], off offset:2304
.Lswakv_skip0:
	s_or_b64 exec, exec, s[16:17]
	v_mov_b32_e32 v28, 0
	v_mov_b32_e32 v29, 0
	v_mov_b32_e32 v30, 0
	v_mov_b32_e32 v31, 0
	v_mov_b32_e32 v32, 0
	v_mov_b32_e32 v33, 0
	v_mov_b32_e32 v34, 0
	v_mov_b32_e32 v35, 0
	v_add_u32_e32 v0, 64, v15
	v_cmp_lt_i32_e32 vcc, -1, v0
	s_and_saveexec_b64 s[16:17], vcc
	s_cbranch_execz .Lswakv_skip1
	v_lshl_add_u64 v[2:3], s[4:5], 0, v[0:1]
	v_mad_u64_u32 v[4:5], s[30:31], v2, s72, v[12:13]
	v_mad_i32_i24 v5, v3, s72, v5
	global_load_dwordx4 v[28:31], v[4:5], off offset:2048
	s_nop 0
	global_load_dwordx4 v[32:35], v[4:5], off offset:2304
.Lswakv_skip1:
	s_or_b64 exec, exec, s[16:17]
	v_mov_b32_e32 v36, 0
	v_mov_b32_e32 v37, 0
	v_mov_b32_e32 v38, 0
	v_mov_b32_e32 v39, 0
	v_mov_b32_e32 v40, 0
	v_mov_b32_e32 v41, 0
	v_mov_b32_e32 v42, 0
	v_mov_b32_e32 v43, 0
	v_add_u32_e32 v0, 128, v15
	v_cmp_lt_i32_e32 vcc, -1, v0
	s_and_saveexec_b64 s[16:17], vcc
	s_cbranch_execz .Lswakv_skip2
	v_lshl_add_u64 v[2:3], s[4:5], 0, v[0:1]
	v_mad_u64_u32 v[4:5], s[30:31], v2, s72, v[12:13]
	v_mad_i32_i24 v5, v3, s72, v5
	global_load_dwordx4 v[36:39], v[4:5], off offset:2048
	s_nop 0
	global_load_dwordx4 v[40:43], v[4:5], off offset:2304
.Lswakv_skip2:
	s_or_b64 exec, exec, s[16:17]
	s_waitcnt vmcnt(4)
	ds_write_b128 v18, v[20:23]
	ds_write_b16 v17, v24 offset:27648
	ds_write_b16_d16_hi v17, v24 offset:28048
	ds_write_b16 v17, v25 offset:28448
	ds_write_b16_d16_hi v17, v25 offset:28848
	ds_write_b16 v17, v26 offset:29248
	ds_write_b16_d16_hi v17, v26 offset:29648
	ds_write_b16 v17, v27 offset:30048
	ds_write_b16_d16_hi v17, v27 offset:30448
	s_waitcnt vmcnt(2)
	ds_write_b128 v18, v[28:31] offset:9216
	ds_write_b16 v17, v32 offset:27776
	ds_write_b16_d16_hi v17, v32 offset:28176
	ds_write_b16 v17, v33 offset:28576
	ds_write_b16_d16_hi v17, v33 offset:28976
	ds_write_b16 v17, v34 offset:29376
	ds_write_b16_d16_hi v17, v34 offset:29776
	ds_write_b16 v17, v35 offset:30176
	ds_write_b16_d16_hi v17, v35 offset:30576
	s_waitcnt vmcnt(0)
	ds_write_b128 v18, v[36:39] offset:18432
	ds_write_b16 v17, v40 offset:27904
	ds_write_b16_d16_hi v17, v40 offset:28304
	ds_write_b16 v17, v41 offset:28704
	ds_write_b16_d16_hi v17, v41 offset:29104
	ds_write_b16 v17, v42 offset:29504
	ds_write_b16_d16_hi v17, v42 offset:29904
	ds_write_b16 v17, v43 offset:30304
	ds_write_b16_d16_hi v17, v43 offset:30704

; __device__ __forceinline__ void moba_unit2(lbyte* lds, const bf16* QKV, bf16* AO, unsigned char* part, unsigned char* part3, const float* km2, const float* rel_bias, int b, int hm, int own) {
;     ...
;         for (int sl = -1; sl < nsel; ++sl) { const unsigned char* pp = sl < 0 ? part3 + (size_t)qid * PART_PITCH : part + (size_t)(qid * 3 + sl) * PART_PITCH;
;             const float ms = *(const float*)(pp + 128), ls = *(const float*)(pp + 132);
;             const float mn = fmaxf(m, ms), a = __builtin_amdgcn_exp2f(m - mn), bq = __builtin_amdgcn_exp2f(ms - mn);
;             l = l * a + ls * bq; m = mn;
; #pragma unroll
;             for (int dt = 0; dt < 2; ++dt)
; #pragma unroll
;                 for (int g = 0; g < 4; ++g) { const u32x2 w = *(const u32x2*)(pp + (32 * dt + 8 * g + 4 * h) * 2);
;                     o[dt][4 * g] = o[dt][4 * g] * a + __uint_as_float(w.x << 16) * bq; o[dt][4 * g + 1] = o[dt][4 * g + 1] * a + __uint_as_float(w.x & 0xffff0000u) * bq;
;                     o[dt][4 * g + 2] = o[dt][4 * g + 2] * a + __uint_as_float(w.y << 16) * bq; o[dt][4 * g + 3] = o[dt][4 * g + 3] * a + __uint_as_float(w.y & 0xffff0000u) * bq; } }
.LBB0_683:
	v_mov_b64_e32 v[40:41], s[0:1]
	v_mad_i64_i32 v[42:43], s[6:7], v0, s73, v[40:41]
	global_load_dwordx2 v[44:45], v[42:43], off offset:128
	v_lshl_add_u64 v[42:43], v[42:43], 0, v[184:185]
	global_load_dwordx2 v[48:49], v[42:43], off
	global_load_dwordx2 v[52:53], v[42:43], off offset:16
	global_load_dwordx2 v[56:57], v[42:43], off offset:32
	global_load_dwordx2 v[60:61], v[42:43], off offset:48
	global_load_dwordx2 v[64:65], v[42:43], off offset:64
	global_load_dwordx2 v[66:67], v[42:43], off offset:80
	global_load_dwordx2 v[68:69], v[42:43], off offset:96
	global_load_dwordx2 v[70:71], v[42:43], off offset:112
	v_max_f32_e32 v27, v19, v19
	s_add_i32 s4, s4, -1
	v_add_u32_e32 v0, 1, v0
	s_cmp_lg_u32 s4, 0
	s_waitcnt vmcnt(8)
	v_max_f32_e32 v9, v44, v44
	v_max_f32_e32 v40, v27, v9
	v_sub_f32_e32 v9, v19, v40
	v_exp_f32_e32 v46, v9
	v_sub_f32_e32 v9, v44, v40
	v_exp_f32_e32 v44, v9
	s_waitcnt vmcnt(7)
	v_lshlrev_b32_e32 v50, 16, v48
	v_and_b32_e32 v51, 0xffff0000, v48
	s_waitcnt vmcnt(6)
	v_lshlrev_b32_e32 v54, 16, v52
	v_and_b32_e32 v55, 0xffff0000, v52
	s_waitcnt vmcnt(4)
	v_and_b32_e32 v47, 0xffff0000, v61
	v_mov_b32_e32 v39, v44
	v_pk_mul_f32 v[50:51], v[44:45], v[50:51] op_sel_hi:[0,1]
	v_pk_mul_f32 v[54:55], v[44:45], v[54:55] op_sel_hi:[0,1]
	v_pk_mul_f32 v[38:39], v[38:39], v[46:47]
	v_lshlrev_b32_e32 v9, 16, v61
	v_mov_b32_e32 v27, v38
	v_mov_b32_e32 v61, v39
	v_pk_fma_f32 v[34:35], v[34:35], v[46:47], v[50:51] op_sel_hi:[1,0,1]
	v_pk_fma_f32 v[30:31], v[30:31], v[46:47], v[54:55] op_sel_hi:[1,0,1]
	v_lshlrev_b32_e32 v48, 16, v49
	v_and_b32_e32 v49, 0xffff0000, v49
	v_lshlrev_b32_e32 v52, 16, v53
	v_and_b32_e32 v53, 0xffff0000, v53
	v_lshlrev_b32_e32 v58, 16, v56
	v_and_b32_e32 v59, 0xffff0000, v56
	v_lshlrev_b32_e32 v56, 16, v57
	v_and_b32_e32 v57, 0xffff0000, v57
	v_lshlrev_b32_e32 v62, 16, v60
	v_and_b32_e32 v63, 0xffff0000, v60
	v_pk_mul_f32 v[48:49], v[44:45], v[48:49] op_sel_hi:[0,1]
	v_pk_mul_f32 v[52:53], v[44:45], v[52:53] op_sel_hi:[0,1]
	v_pk_mul_f32 v[58:59], v[44:45], v[58:59] op_sel_hi:[0,1]
	v_pk_mul_f32 v[56:57], v[44:45], v[56:57] op_sel_hi:[0,1]
	v_pk_mul_f32 v[62:63], v[44:45], v[62:63] op_sel_hi:[0,1]
	v_pk_fma_f32 v[32:33], v[32:33], v[46:47], v[48:49] op_sel_hi:[1,0,1]
	v_pk_fma_f32 v[28:29], v[28:29], v[46:47], v[52:53] op_sel_hi:[1,0,1]
	v_pk_fma_f32 v[24:25], v[24:25], v[46:47], v[58:59] op_sel_hi:[1,0,1]
	v_pk_fma_f32 v[22:23], v[22:23], v[46:47], v[56:57] op_sel_hi:[1,0,1]
	v_pk_fma_f32 v[20:21], v[20:21], v[46:47], v[62:63] op_sel_hi:[1,0,1]
	v_mov_b32_e32 v19, v44
	v_mul_f32_e32 v60, v44, v9
	v_mul_f32_e32 v26, v26, v46
	v_mul_f32_e32 v8, v8, v46
	v_mov_b32_e32 v37, v45
	v_pk_add_f32 v[26:27], v[26:27], v[60:61]
	s_waitcnt vmcnt(3)
	v_lshlrev_b32_e32 v48, 16, v64
	v_and_b32_e32 v49, 0xffff0000, v64
	v_lshlrev_b32_e32 v38, 16, v65
	v_and_b32_e32 v39, 0xffff0000, v65
	s_waitcnt vmcnt(2)
	v_lshlrev_b32_e32 v52, 16, v66
	v_and_b32_e32 v53, 0xffff0000, v66
	v_lshlrev_b32_e32 v50, 16, v67
	v_and_b32_e32 v51, 0xffff0000, v67
	s_waitcnt vmcnt(1)
	v_lshlrev_b32_e32 v56, 16, v68
	v_and_b32_e32 v57, 0xffff0000, v68
	v_lshlrev_b32_e32 v54, 16, v69
	v_and_b32_e32 v55, 0xffff0000, v69
	s_waitcnt vmcnt(0)
	v_lshlrev_b32_e32 v58, 16, v70
	v_and_b32_e32 v59, 0xffff0000, v70
	v_and_b32_e32 v47, 0xffff0000, v71
	v_pk_mul_f32 v[48:49], v[44:45], v[48:49] op_sel_hi:[0,1]
	v_pk_mul_f32 v[38:39], v[44:45], v[38:39] op_sel_hi:[0,1]
	v_pk_mul_f32 v[52:53], v[44:45], v[52:53] op_sel_hi:[0,1]
	v_pk_mul_f32 v[50:51], v[44:45], v[50:51] op_sel_hi:[0,1]
	v_pk_mul_f32 v[56:57], v[44:45], v[56:57] op_sel_hi:[0,1]
	v_pk_mul_f32 v[54:55], v[44:45], v[54:55] op_sel_hi:[0,1]
	v_pk_mul_f32 v[58:59], v[44:45], v[58:59] op_sel_hi:[0,1]
	v_lshlrev_b32_e32 v9, 16, v71
	v_pk_mul_f32 v[18:19], v[18:19], v[46:47]
	v_mul_f32_e32 v42, v44, v9
	v_mov_b32_e32 v9, v18
	v_mov_b32_e32 v43, v19
	v_pk_fma_f32 v[16:17], v[16:17], v[46:47], v[48:49] op_sel_hi:[1,0,1]
	v_pk_fma_f32 v[14:15], v[14:15], v[46:47], v[38:39] op_sel_hi:[1,0,1]
	v_pk_fma_f32 v[12:13], v[12:13], v[46:47], v[52:53] op_sel_hi:[1,0,1]
	v_pk_fma_f32 v[10:11], v[10:11], v[46:47], v[50:51] op_sel_hi:[1,0,1]
	v_pk_fma_f32 v[2:3], v[2:3], v[46:47], v[56:57] op_sel_hi:[1,0,1]
	v_pk_fma_f32 v[6:7], v[6:7], v[46:47], v[54:55] op_sel_hi:[1,0,1]
	v_pk_fma_f32 v[4:5], v[4:5], v[46:47], v[58:59] op_sel_hi:[1,0,1]
	v_mov_b32_e32 v47, v44
	v_pk_add_f32 v[8:9], v[8:9], v[42:43]
	v_pk_mul_f32 v[18:19], v[36:37], v[46:47]
	v_mov_b32_e32 v38, v27
	v_add_f32_e32 v36, v18, v19
	v_mov_b32_e32 v18, v9
	v_mov_b32_e32 v19, v40
	s_cbranch_scc1 .LBB0_683
	s_branch .LBB0_551
